# attention QK section (first unrolled key tile): K fragment LDS reads prefetched 3 fragments ahead through v242-v253 (compiler had 1 ahead); on top of v57
# speedup vs baseline: 1.0139x; 1.0042x over previous
; #define MFMA16(a, b, c) __builtin_amdgcn_mfma_f32_16x16x32_bf16((a), (b), (c), 0, 0, 0)
; __device__ __forceinline__ void attn_unit(const WS& ws, int u, bool dry = false) {
;     ...
;   auto loadg = [&](int kt, u32x4 (&kreg)[3], u32x4 (&vreg)[2]) {
; #pragma unroll
;     for (int i = 0; i < 3; ++i) {
;       const int ci = tid + 256 * i; const int key = ci / 12, ch = ci - key * 12;
;       int gk = 64 * kt + key; if (gk > T_ - 1) gk = T_ - 1;
;       const bf16_t* src = ch < 8 ? ws.KN + (size_t)(b * T_ + gk) * 1024 + hd * 64 + ch * 8
;                                  : ws.KR + (size_t)(b * T_ + gk) * 32 + (ch - 8) * 8;
;       kreg[i] = *(const u32x4*)src;
;     }
;     ...
;     { const int kn = kt + 2 < nkt2 ? kt + 2 : nkt2 - 1; loadg(kn, kreg, vreg); }
;     const bf16_t* Kb = Kt + buf * 64 * 104;
;     const bf16_t* Vb = Vl + buf * 64 * 72;
;     f32x4 s[4][2];
; #pragma unroll
;     for (int mt = 0; mt < 4; ++mt) {
;       s[mt][0] = (f32x4){0.f, 0.f, 0.f, 0.f}; s[mt][1] = (f32x4){0.f, 0.f, 0.f, 0.f};
; #pragma unroll
;       for (int ks = 0; ks < 3; ++ks) {
;         const bf16x8 kf = *(const bf16x8*)(Kb + (16 * mt + lr) * 104 + 32 * ks + 8 * lq);
;         s[mt][0] = MFMA16(kf, xq[0][ks], s[mt][0]);
;         s[mt][1] = MFMA16(kf, xq[1][ks], s[mt][1]);
;       }
;     }
.LBB0_863:
	ds_read_b128 v[242:245], v183
	ds_read_b128 v[246:249], v183 offset:64
	ds_read_b128 v[250:253], v183 offset:128
	s_add_i32 s4, s35, -1
	s_min_i32 s4, s4, s37
	s_lshl_b32 s4, s4, 6
	s_waitcnt lgkmcnt(2)
	v_mfma_f32_16x16x32_bf16 v[58:61], v[242:245], v[0:3], 0
	s_ashr_i32 s5, s4, 31
	s_lshl_b64 s[6:7], s[4:5], 1
	s_add_i32 s5, s35, -3
	v_mfma_f32_16x16x32_bf16 v[50:53], v[242:245], v[14:17], 0
	ds_read_b128 v[242:245], v183 offset:3328
	s_cmp_lt_u32 s5, s34
	s_waitcnt lgkmcnt(2)
	v_mfma_f32_16x16x32_bf16 v[58:61], v[246:249], v[4:7], v[58:61]
	v_mfma_f32_16x16x32_bf16 v[50:53], v[246:249], v[8:11], v[50:53]
	ds_read_b128 v[246:249], v183 offset:3392
	s_waitcnt lgkmcnt(2)
	v_mfma_f32_16x16x32_bf16 v[98:101], v[250:253], v[30:33], v[50:53]
	s_nop 3
	v_mfma_f32_16x16x32_bf16 v[114:117], v[250:253], v[22:25], v[58:61]
	ds_read_b128 v[250:253], v183 offset:3456
	s_nop 2
	v_add_u32_e32 v58, s4, v171
	s_waitcnt lgkmcnt(2)
	v_mfma_f32_16x16x32_bf16 v[54:57], v[242:245], v[0:3], 0
	v_min_i32_e32 v86, 0x80f, v58
	v_add_u32_e32 v86, s66, v86
	v_ashrrev_i32_e32 v87, 31, v86
	v_mfma_f32_16x16x32_bf16 v[58:61], v[242:245], v[14:17], 0
	ds_read_b128 v[242:245], v183 offset:6656
	v_lshlrev_b64 v[88:89], 11, v[86:87]
	v_lshlrev_b64 v[86:87], 6, v[86:87]
	s_waitcnt lgkmcnt(2)
	v_mfma_f32_16x16x32_bf16 v[54:57], v[246:249], v[4:7], v[54:57]
	v_lshl_add_u64 v[102:103], v[154:155], 0, v[88:89]
	v_mfma_f32_16x16x32_bf16 v[58:61], v[246:249], v[8:11], v[58:61]
	ds_read_b128 v[246:249], v183 offset:6720
	v_lshl_add_u64 v[50:51], v[152:153], 0, v[86:87]
	v_lshl_add_u64 v[50:51], v[50:51], 0, s[86:87]
	s_waitcnt lgkmcnt(2)
	v_mfma_f32_16x16x32_bf16 v[118:121], v[250:253], v[22:25], v[54:57]
	v_cndmask_b32_e64 v51, v51, v103, s[38:39]
	v_cndmask_b32_e64 v50, v50, v102, s[38:39]
	global_load_dwordx4 v[50:53], v[50:51], off
	v_add_u32_e32 v54, s4, v172
	v_mfma_f32_16x16x32_bf16 v[102:105], v[250:253], v[30:33], v[58:61]
	ds_read_b128 v[250:253], v183 offset:6784
	v_min_i32_e32 v82, 0x80f, v54
	v_add_u32_e32 v106, s66, v82
	s_waitcnt lgkmcnt(2)
	v_mfma_f32_16x16x32_bf16 v[58:61], v[242:245], v[0:3], 0
	v_ashrrev_i32_e32 v107, 31, v106
	v_lshlrev_b64 v[108:109], 11, v[106:107]
	v_lshlrev_b64 v[106:107], 6, v[106:107]
	v_mfma_f32_16x16x32_bf16 v[82:85], v[242:245], v[14:17], 0
	ds_read_b128 v[242:245], v183 offset:9984
	v_lshl_add_u64 v[106:107], v[156:157], 0, v[106:107]
	v_lshl_add_u64 v[108:109], v[158:159], 0, v[108:109]
	v_lshl_add_u64 v[106:107], v[106:107], 0, s[86:87]
	s_waitcnt lgkmcnt(2)
	v_mfma_f32_16x16x32_bf16 v[58:61], v[246:249], v[4:7], v[58:61]
	v_cndmask_b32_e64 v107, v107, v109, s[40:41]
	v_cndmask_b32_e64 v106, v106, v108, s[40:41]
	v_mfma_f32_16x16x32_bf16 v[82:85], v[246:249], v[8:11], v[82:85]
	ds_read_b128 v[246:249], v183 offset:10048
	global_load_dwordx4 v[54:57], v[106:107], off
	s_waitcnt lgkmcnt(2)
	v_mfma_f32_16x16x32_bf16 v[122:125], v[250:253], v[22:25], v[58:61]
	s_nop 2
	v_add_u32_e32 v58, s4, v173
	v_min_i32_e32 v58, 0x80f, v58
	v_mfma_f32_16x16x32_bf16 v[110:113], v[250:253], v[30:33], v[82:85]
	ds_read_b128 v[250:253], v183 offset:10112
	v_add_u32_e32 v126, s66, v58
	v_ashrrev_i32_e32 v127, 31, v126
	v_lshlrev_b64 v[86:87], 11, v[126:127]
	v_lshl_add_u64 v[130:131], v[162:163], 0, v[86:87]
	v_lshlrev_b64 v[86:87], 6, v[126:127]
	s_waitcnt lgkmcnt(2)
	v_mfma_f32_16x16x32_bf16 v[58:61], v[242:245], v[0:3], 0
	v_lshl_add_u64 v[126:127], v[160:161], 0, v[86:87]
	v_lshl_add_u64 v[132:133], v[126:127], 0, s[86:87]
	v_cndmask_b32_e64 v131, v133, v131, s[42:43]
	v_mfma_f32_16x16x32_bf16 v[86:89], v[242:245], v[14:17], 0
	v_cndmask_b32_e64 v130, v132, v130, s[42:43]
	s_waitcnt lgkmcnt(1)
	v_mfma_f32_16x16x32_bf16 v[126:129], v[246:249], v[4:7], v[58:61]
	s_nop 2
	global_load_dwordx4 v[58:61], v[130:131], off
	v_mfma_f32_16x16x32_bf16 v[130:133], v[246:249], v[8:11], v[86:89]
	v_lshl_add_u64 v[82:83], v[148:149], 0, s[6:7]
	v_lshl_add_u64 v[84:85], v[150:151], 0, s[6:7]
	s_nop 0
	global_load_dwordx4 v[86:89], v[82:83], off
	s_nop 0
	global_load_dwordx4 v[82:85], v[84:85], off
	s_waitcnt lgkmcnt(0)
	v_mfma_f32_16x16x32_bf16 v[126:129], v[250:253], v[22:25], v[126:129]
	v_mfma_f32_16x16x32_bf16 v[106:109], v[250:253], v[30:33], v[130:133]
	s_cbranch_scc1 .LBB0_865
; __device__ __forceinline__ void attn_unit(const WS& ws, int u, bool dry = false) {
;     ...
;     if (kt >= 2 * qb) {
; #pragma unroll
;       for (int mt = 0; mt < 4; ++mt)
; #pragma unroll
;         for (int nt = 0; nt < 2; ++nt)
; #pragma unroll
;           for (int jj = 0; jj < 4; ++jj) {
;             const int key = 64 * kt + 16 * mt + 4 * lq + jj;
;             if (key > qi[nt]) s[mt][nt][jj] = -INFINITY;
;           }
;     }
	v_cmp_gt_i32_e32 vcc, v185, v169
	s_nop 0
	v_mov_b32_e32 v130, s17
	v_cmp_lt_i32_e64 s[44:45], v185, v169
	v_cndmask_b32_e32 v130, v114, v130, vcc
	v_add_u32_e32 v131, 2, v185
	v_cndmask_b32_e64 v114, v130, v114, s[44:45]
	v_cndmask_b32_e64 v115, v194, v115, s[44:45]
	v_cmp_le_i32_e64 s[44:45], v131, v169
	v_add_u32_e32 v132, 3, v185
	v_mov_b32_e32 v130, s17
	v_cndmask_b32_e64 v116, v194, v116, s[44:45]
	v_cmp_le_i32_e64 s[44:45], v132, v169
	v_add_u32_e32 v133, 19, v185
	v_add_u32_e32 v134, 35, v185
	v_cndmask_b32_e64 v117, v194, v117, s[44:45]
	v_cmp_gt_i32_e64 s[44:45], v185, v13
	s_nop 1
	v_cndmask_b32_e64 v130, v98, v130, s[44:45]
	v_cmp_lt_i32_e64 s[44:45], v185, v13
	s_nop 1
	v_cndmask_b32_e64 v98, v130, v98, s[44:45]
	v_cndmask_b32_e64 v99, v194, v99, s[44:45]
	v_cmp_le_i32_e64 s[44:45], v131, v13
	v_add_u32_e32 v130, 16, v185
	v_add_u32_e32 v131, 17, v185
	v_cndmask_b32_e64 v100, v194, v100, s[44:45]
	v_cmp_le_i32_e64 s[44:45], v132, v13
	v_add_u32_e32 v132, 18, v185
	s_nop 0
	v_cndmask_b32_e64 v101, v194, v101, s[44:45]
	v_cmp_gt_i32_e64 s[44:45], v130, v169
	v_mov_b32_e32 v130, s17
	v_cndmask_b32_e32 v102, v102, v130, vcc
	v_cmp_le_i32_e32 vcc, v131, v13
	v_cndmask_b32_e64 v118, v118, v130, s[44:45]
	v_cmp_le_i32_e64 s[44:45], v131, v169
	v_cndmask_b32_e32 v103, v194, v103, vcc
	v_cmp_le_i32_e32 vcc, v132, v13
	v_add_u32_e32 v131, 32, v185
	v_cndmask_b32_e64 v119, v194, v119, s[44:45]
	v_cndmask_b32_e32 v104, v194, v104, vcc
	v_cmp_le_i32_e32 vcc, v133, v13
	v_cmp_le_i32_e64 s[44:45], v132, v169
	v_add_u32_e32 v132, 33, v185
	v_cndmask_b32_e32 v105, v194, v105, vcc
	v_cmp_gt_i32_e32 vcc, v131, v169
	v_cndmask_b32_e64 v120, v194, v120, s[44:45]
	v_cmp_le_i32_e64 s[44:45], v133, v169
	v_cndmask_b32_e32 v122, v122, v130, vcc
	v_cmp_le_i32_e32 vcc, v132, v169
	v_add_u32_e32 v133, 34, v185
	v_cndmask_b32_e64 v121, v194, v121, s[44:45]
	v_cndmask_b32_e32 v123, v194, v123, vcc
	v_cmp_le_i32_e32 vcc, v133, v169
	s_nop 1
	v_cndmask_b32_e32 v124, v194, v124, vcc
	v_cmp_le_i32_e32 vcc, v134, v169
	s_nop 1
	v_cndmask_b32_e32 v125, v194, v125, vcc
	v_cmp_gt_i32_e32 vcc, v131, v13
	v_add_u32_e32 v131, 48, v185
	s_nop 0
	v_cndmask_b32_e32 v110, v110, v130, vcc
	v_cmp_le_i32_e32 vcc, v132, v13
	v_add_u32_e32 v132, 49, v185
	s_nop 0
	v_cndmask_b32_e32 v111, v194, v111, vcc
	v_cmp_le_i32_e32 vcc, v133, v13
	v_add_u32_e32 v133, 50, v185
	s_nop 0
	v_cndmask_b32_e32 v112, v194, v112, vcc
	v_cmp_le_i32_e32 vcc, v134, v13
	v_add_u32_e32 v134, 51, v185
	s_nop 0
	v_cndmask_b32_e32 v113, v194, v113, vcc
	v_cmp_gt_i32_e32 vcc, v131, v169
	s_nop 1
	v_cndmask_b32_e32 v126, v126, v130, vcc
	v_cmp_le_i32_e32 vcc, v132, v169
	s_nop 1
	v_cndmask_b32_e32 v127, v194, v127, vcc
	v_cmp_le_i32_e32 vcc, v133, v169
	s_nop 1
	v_cndmask_b32_e32 v128, v194, v128, vcc
	v_cmp_le_i32_e32 vcc, v134, v169
	s_nop 1
	v_cndmask_b32_e32 v129, v194, v129, vcc
	v_cmp_gt_i32_e32 vcc, v131, v13
	s_nop 1
	v_cndmask_b32_e32 v106, v106, v130, vcc
	v_cmp_le_i32_e32 vcc, v132, v13
	s_nop 1
	v_cndmask_b32_e32 v107, v194, v107, vcc
	v_cmp_le_i32_e32 vcc, v133, v13
	s_nop 1
	v_cndmask_b32_e32 v108, v194, v108, vcc
	v_cmp_le_i32_e32 vcc, v134, v13
	s_nop 1
	v_cndmask_b32_e32 v109, v194, v109, vcc
